# GQA loop: first PV transposed-V LDS reads issued two MFMAs before the end of QK^T (into registers free in that window) to hide LDS latency at the PV segment start
# baseline (speedup 1.0000x reference)
; #define SBAR() __builtin_amdgcn_sched_barrier(0)
; #define SLOAD(i, k0) do { sr_[i].vs0 = *reinterpret_cast<const bf16x8*>(vptr + (size_t)((k0) + sr) * vstr); \
;     sr_[i].vs1 = *reinterpret_cast<const bf16x8*>(vptr + (size_t)((k0) + 32 + sr) * vstr); \
;     sr_[i].ks0 = *reinterpret_cast<const bf16x8*>(kptr + (size_t)((k0) + sr) * kstr); \
;     sr_[i].ks1 = *reinterpret_cast<const bf16x8*>(kptr + (size_t)((k0) + 32 + sr) * kstr); } while (0)
; template <int NDQ, int NDV> ...
;     ...
;     SBAR(); qkt<NDQ>(pB0, pB1, K_lds + SHM_K, qr, r32, hi);
;     finishSM(pA0, pA1, alA, l_reg, pa0, pa1, pa2, pa3); SBAR();
;     SLOAD(SO, (j + 2) * 64); SBAR();
;     pv_d0<NDV>(o, vb0, pa0, pa1, pa2, pa3); partialSM(pB0, pB1, m_reg, mnB, alB, Cs, thr);
.LBB0_2123:
	ds_read_b128 v[64:67], v199 offset:49152
	ds_read_b128 v[68:71], v199 offset:57344
	ds_read_b128 v[216:219], v200 offset:49152
	ds_read_b128 v[220:223], v200 offset:57344
	v_add_f32_e32 v161, 0, v236
	v_add_f32_e32 v161, v237, v161
	s_waitcnt lgkmcnt(3)
	v_mfma_f32_32x32x16_bf16 v[80:95], v[64:67], v[124:127], 0
	v_add_f32_e32 v161, v238, v161
	v_add_f32_e32 v161, v239, v161
	v_add_f32_e32 v161, v240, v161
	v_add_f32_e32 v161, v241, v161
	v_add_f32_e32 v161, v242, v161
	v_add_f32_e32 v161, v243, v161
	s_waitcnt lgkmcnt(2)
	v_mfma_f32_32x32x16_bf16 v[64:79], v[68:71], v[124:127], 0
	v_add_f32_e32 v161, v244, v161
	v_add_f32_e32 v161, v245, v161
	v_add_f32_e32 v161, v246, v161
	v_add_f32_e32 v161, v247, v161
	v_exp_f32_e32 v154, v154
	s_waitcnt lgkmcnt(1)
	v_mfma_f32_32x32x16_bf16 v[80:95], v[216:219], v[120:123], v[80:95]
	v_add_f32_e32 v161, v248, v161
	v_exp_f32_e32 v155, v155
	v_add_f32_e32 v161, v249, v161
	v_exp_f32_e32 v152, v152
	s_waitcnt lgkmcnt(0)
	v_mfma_f32_32x32x16_bf16 v[64:79], v[220:223], v[120:123], v[64:79]
	ds_read_b128 v[216:219], v201 offset:49152
	ds_read_b128 v[220:223], v201 offset:57344
	v_add_f32_e32 v161, v250, v161
	v_exp_f32_e32 v153, v153
	v_add_f32_e32 v161, v251, v161
	v_exp_f32_e32 v148, v148
	s_waitcnt lgkmcnt(1)
	v_mfma_f32_32x32x16_bf16 v[80:95], v[216:219], v[116:119], v[80:95]
	v_add_f32_e32 v161, v154, v161
	v_exp_f32_e32 v149, v149
	v_add_f32_e32 v161, v155, v161
	v_exp_f32_e32 v146, v146
	s_waitcnt lgkmcnt(0)
	v_mfma_f32_32x32x16_bf16 v[64:79], v[220:223], v[116:119], v[64:79]
	ds_read_b128 v[216:219], v202 offset:49152
	ds_read_b128 v[220:223], v202 offset:57344
	v_add_f32_e32 v161, v152, v161
	v_exp_f32_e32 v147, v147
	v_add_f32_e32 v161, v153, v161
	v_exp_f32_e32 v144, v144
	s_waitcnt lgkmcnt(1)
	v_mfma_f32_32x32x16_bf16 v[80:95], v[216:219], v[112:115], v[80:95]
	v_add_f32_e32 v161, v148, v161
	v_exp_f32_e32 v145, v145
	v_add_f32_e32 v161, v149, v161
	v_exp_f32_e32 v158, v158
	s_waitcnt lgkmcnt(0)
	v_mfma_f32_32x32x16_bf16 v[64:79], v[220:223], v[112:115], v[64:79]
	ds_read_b128 v[216:219], v203 offset:49152
	ds_read_b128 v[220:223], v203 offset:57344
	v_add_f32_e32 v161, v146, v161
	v_exp_f32_e32 v159, v159
	v_add_f32_e32 v161, v147, v161
	v_exp_f32_e32 v156, v156
	s_waitcnt lgkmcnt(1)
	v_mfma_f32_32x32x16_bf16 v[80:95], v[216:219], v[108:111], v[80:95]
	v_add_f32_e32 v161, v144, v161
	v_exp_f32_e32 v157, v157
	v_add_f32_e32 v161, v145, v161
	v_exp_f32_e32 v150, v150
	s_waitcnt lgkmcnt(0)
	v_mfma_f32_32x32x16_bf16 v[64:79], v[220:223], v[108:111], v[64:79]
	ds_read_b128 v[216:219], v204 offset:49152
	ds_read_b128 v[220:223], v204 offset:57344
	v_add_f32_e32 v161, v158, v161
	v_exp_f32_e32 v151, v151
	v_add_f32_e32 v161, v159, v161
	v_add_f32_e32 v161, v156, v161
	v_add_f32_e32 v161, v157, v161
	s_waitcnt lgkmcnt(1)
	v_mfma_f32_32x32x16_bf16 v[80:95], v[216:219], v[104:107], v[80:95]
	v_add_f32_e32 v161, v150, v161
	v_add_f32_e32 v208, v151, v161
	v_mov_b32_e32 v209, v208
	v_cvt_pk_bf16_f32 v210, v236, v237
	v_cvt_pk_bf16_f32 v211, v238, v239
	v_cvt_pk_bf16_f32 v212, v240, v241
	s_waitcnt lgkmcnt(0)
	v_mfma_f32_32x32x16_bf16 v[64:79], v[220:223], v[104:107], v[64:79]
	ds_read_b128 v[216:219], v205 offset:49152
	ds_read_b128 v[220:223], v205 offset:57344
	v_permlane32_swap_b32_e32 v208, v209
	v_cvt_pk_bf16_f32 v213, v242, v243
	v_cvt_pk_bf16_f32 v170, v244, v245
	v_cvt_pk_bf16_f32 v171, v246, v247
	v_permlane32_swap_b32_e32 v210, v212
	v_cvt_pk_bf16_f32 v172, v248, v249
	s_waitcnt lgkmcnt(1)
	v_mfma_f32_32x32x16_bf16 v[80:95], v[216:219], v[100:103], v[80:95]
	v_cvt_pk_bf16_f32 v173, v250, v251
	v_cvt_pk_bf16_f32 v162, v154, v155
	v_cvt_pk_bf16_f32 v163, v152, v153
	v_cvt_pk_bf16_f32 v164, v148, v149
	v_cvt_pk_bf16_f32 v165, v146, v147
	v_cvt_pk_bf16_f32 v166, v144, v145
	s_waitcnt lgkmcnt(0)
	v_mfma_f32_32x32x16_bf16 v[64:79], v[220:223], v[100:103], v[64:79]
	ds_read_b128 v[216:219], v206 offset:49152
	ds_read_b128 v[220:223], v206 offset:57344
	ds_read_b64_tr_b16 v[236:237], v194 offset:0
	ds_read_b64_tr_b16 v[238:239], v194 offset:0x800
	ds_read_b64_tr_b16 v[240:241], v194 offset:0x1000
	ds_read_b64_tr_b16 v[242:243], v194 offset:0x1800
	ds_read_b64_tr_b16 v[244:245], v194 offset:0x2000
	ds_read_b64_tr_b16 v[246:247], v194 offset:0x2800
	ds_read_b64_tr_b16 v[248:249], v194 offset:0x3000
	ds_read_b64_tr_b16 v[250:251], v194 offset:0x3800
	v_cvt_pk_bf16_f32 v167, v158, v159
	v_cvt_pk_bf16_f32 v168, v156, v157
	v_cvt_pk_bf16_f32 v169, v150, v151
	v_permlane32_swap_b32_e32 v211, v213
	v_permlane32_swap_b32_e32 v170, v172
	v_permlane32_swap_b32_e32 v171, v173
	s_waitcnt lgkmcnt(9)
	v_mfma_f32_32x32x16_bf16 v[80:95], v[216:219], v[96:99], v[80:95]
	v_permlane32_swap_b32_e32 v162, v164
	v_permlane32_swap_b32_e32 v163, v165
	v_permlane32_swap_b32_e32 v166, v168
	v_permlane32_swap_b32_e32 v167, v169
	s_waitcnt lgkmcnt(8)
	v_mfma_f32_32x32x16_bf16 v[64:79], v[220:223], v[96:99], v[64:79]
	v_add_co_u32_e32 v148, vcc, s50, v184
	s_nop 1
	v_addc_co_u32_e32 v149, vcc, -1, v185, vcc
	v_add_co_u32_e32 v152, vcc, s51, v184
	s_nop 1
	v_addc_co_u32_e32 v153, vcc, -1, v185, vcc
	global_load_dwordx4 v[144:147], v[148:149], off
	s_nop 0
	global_load_dwordx4 v[148:151], v[148:149], off offset:-512
	s_nop 0
	global_load_dwordx4 v[156:159], v[152:153], off
	s_nop 0
	global_load_dwordx4 v[152:155], v[152:153], off offset:-512
	s_waitcnt vmcnt(4)
	ds_write_b128 v195, v[140:143] offset:32768
	ds_write_b128 v196, v[132:135] offset:32768
	s_waitcnt lgkmcnt(8)
; #define SBAR() __builtin_amdgcn_sched_barrier(0)
; #define SWRITE(b, i) do { *(LAS bf16x8*)(V_lds + (b) * SHM_V + vst0) = sr_[i].vs0;          \
;     *(LAS bf16x8*)(V_lds + (b) * SHM_V + vst1) = sr_[i].vs1; const int kc = sc * 2;               \
;     *(LAS bf16x8*)(K_lds + (b) * SHM_K + KSWZ(sr, kc)) = sr_[i].ks0;                       \
;     *(LAS bf16x8*)(K_lds + (b) * SHM_K + KSWZ(32 + sr, kc)) = sr_[i].ks1; } while (0)
; #define SWAIT() asm volatile("s_waitcnt vmcnt(4)" ::: "memory")
; template <int D0> __device__ __forceinline__ void pv_one(f32x16& od, int vb, bf16x8 pa0, bf16x8 pa1, bf16x8 pa2, bf16x8 pa3) {
;   const s16x4 l0 = tr_read<v_rd_off(D0, 0, 0)>(vb), h0 = tr_read<v_rd_off(D0, 0, 1)>(vb), l1 = tr_read<v_rd_off(D0, 1, 0)>(vb), h1 = tr_read<v_rd_off(D0, 1, 1)>(vb);
;   const s16x4 l2 = tr_read<v_rd_off(D0, 2, 0)>(vb), h2 = tr_read<v_rd_off(D0, 2, 1)>(vb), l3 = tr_read<v_rd_off(D0, 3, 0)>(vb), h3 = tr_read<v_rd_off(D0, 3, 1)>(vb);
;   asm volatile("s_waitcnt lgkmcnt(0)" ::: "memory"); SBAR();
;     ...
;   od = __builtin_amdgcn_mfma_f32_32x32x16_bf16(pa0, PK(l0, h0), od, 0, 0, 0);
;   od = __builtin_amdgcn_mfma_f32_32x32x16_bf16(pa1, PK(l1, h1), od, 0, 0, 0);
;   od = __builtin_amdgcn_mfma_f32_32x32x16_bf16(pa2, PK(l2, h2), od, 0, 0, 0);
;   od = __builtin_amdgcn_mfma_f32_32x32x16_bf16(pa3, PK(l3, h3), od, 0, 0, 0);
; template <int NDQ, int NDV> ...
;     ...
;     pv_d0<NDV>(o, vb0, pa0, pa1, pa2, pa3); partialSM(pB0, pB1, m_reg, mnB, alB, Cs, thr);
;     __syncthreads(); SWAIT(); SWRITE(0, SE);
	v_mfma_f32_32x32x16_bf16 v[0:15], v[210:213], v[236:239], v[0:15]
	ds_read_b64_tr_b16 v[214:215], v194 offset:0x200
	ds_read_b64_tr_b16 v[216:217], v194 offset:0xa00
	v_max_f32_e32 v161, v81, v81
	v_max_f32_e32 v174, v80, v80
	v_max_f32_e32 v161, v174, v161
	v_max3_f32 v161, v161, v82, v83
	v_max3_f32 v161, v161, v84, v85
	v_max3_f32 v161, v161, v86, v87
	s_waitcnt lgkmcnt(8)
	v_mfma_f32_32x32x16_bf16 v[0:15], v[170:173], v[240:243], v[0:15]
	ds_read_b64_tr_b16 v[218:219], v194 offset:0x1200
	ds_read_b64_tr_b16 v[220:221], v194 offset:0x1a00
	v_max3_f32 v161, v161, v88, v89
	v_max3_f32 v161, v161, v90, v91
	v_max3_f32 v161, v161, v92, v93
	v_max3_f32 v161, v161, v94, v95
	v_max3_f32 v161, v161, v64, v65
	v_max3_f32 v161, v161, v66, v67
	s_waitcnt lgkmcnt(8)
	v_mfma_f32_32x32x16_bf16 v[0:15], v[162:165], v[244:247], v[0:15]
	ds_read_b64_tr_b16 v[222:223], v194 offset:0x2200
	ds_read_b64_tr_b16 v[224:225], v194 offset:0x2a00
	ds_read_b64_tr_b16 v[230:231], v194 offset:0x3200
	ds_read_b64_tr_b16 v[232:233], v194 offset:0x3a00
	v_max3_f32 v161, v161, v68, v69
	v_max3_f32 v161, v161, v70, v71
	v_max3_f32 v161, v161, v72, v73
	v_max3_f32 v161, v161, v74, v75
	v_max3_f32 v161, v161, v76, v77
	v_max3_f32 v161, v161, v78, v79
	s_waitcnt lgkmcnt(10)
	v_mfma_f32_32x32x16_bf16 v[0:15], v[166:169], v[248:251], v[0:15]
	v_mov_b32_e32 v174, v161
	s_nop 1
	v_permlane32_swap_b32_e32 v161, v174
	v_max_f32_e32 v175, v174, v174
	v_max_f32_e32 v161, v161, v161
	v_max_f32_e32 v161, v161, v175
	s_waitcnt lgkmcnt(6)
	v_mfma_f32_32x32x16_bf16 v[48:63], v[210:213], v[214:217], v[48:63]
	ds_read_b64_tr_b16 v[214:215], v194 offset:0x400
	ds_read_b64_tr_b16 v[216:217], v194 offset:0xc00
	v_max_f32_e32 v235, v160, v160
	v_sub_f32_e32 v175, v161, v160
	v_max_f32_e32 v161, v235, v161
	v_sub_f32_e32 v235, v160, v161
	v_mul_f32_e32 v235, 0x3e0293ee, v235
	s_waitcnt lgkmcnt(6)
	v_mfma_f32_32x32x16_bf16 v[48:63], v[170:173], v[218:221], v[48:63]
	ds_read_b64_tr_b16 v[218:219], v194 offset:0x1400
	ds_read_b64_tr_b16 v[220:221], v194 offset:0x1c00
	v_exp_f32_e32 v235, v235
	v_cmp_ge_f32_e32 vcc, s48, v175
	s_cmp_eq_u64 vcc, exec
	s_cselect_b64 s[2:3], -1, 0
	v_cndmask_b32_e64 v234, v161, v160, s[2:3]
	s_waitcnt lgkmcnt(6)
	v_mfma_f32_32x32x16_bf16 v[48:63], v[162:165], v[222:225], v[48:63]
	ds_read_b64_tr_b16 v[222:223], v194 offset:0x2400
	ds_read_b64_tr_b16 v[224:225], v194 offset:0x2c00
	ds_read_b64_tr_b16 v[226:227], v194 offset:0x3400
	ds_read_b64_tr_b16 v[228:229], v194 offset:0x3c00
	v_mul_f32_e32 v175, 0xbe0293ee, v234
	v_fmamk_f32 v80, v80, 0x3e0293ee, v175
	v_fmamk_f32 v81, v81, 0x3e0293ee, v175
	v_fmamk_f32 v82, v82, 0x3e0293ee, v175
	v_fmamk_f32 v83, v83, 0x3e0293ee, v175
	v_fmamk_f32 v84, v84, 0x3e0293ee, v175
	s_waitcnt lgkmcnt(8)
	v_mfma_f32_32x32x16_bf16 v[48:63], v[166:169], v[230:233], v[48:63]
	v_fmamk_f32 v85, v85, 0x3e0293ee, v175
	v_fmamk_f32 v86, v86, 0x3e0293ee, v175
	v_fmamk_f32 v87, v87, 0x3e0293ee, v175
	v_fmamk_f32 v88, v88, 0x3e0293ee, v175
	v_fmamk_f32 v89, v89, 0x3e0293ee, v175
	v_fmamk_f32 v90, v90, 0x3e0293ee, v175
	s_waitcnt lgkmcnt(6)
	v_mfma_f32_32x32x16_bf16 v[32:47], v[210:213], v[214:217], v[32:47]
	ds_read_b64_tr_b16 v[214:215], v194 offset:0x600
	ds_read_b64_tr_b16 v[216:217], v194 offset:0xe00
	v_fmamk_f32 v91, v91, 0x3e0293ee, v175
	v_fmamk_f32 v92, v92, 0x3e0293ee, v175
	v_fmamk_f32 v93, v93, 0x3e0293ee, v175
	v_fmamk_f32 v94, v94, 0x3e0293ee, v175
	v_fmamk_f32 v95, v95, 0x3e0293ee, v175
	s_waitcnt lgkmcnt(6)
	v_mfma_f32_32x32x16_bf16 v[32:47], v[170:173], v[218:221], v[32:47]
	ds_read_b64_tr_b16 v[218:219], v194 offset:0x1600
	ds_read_b64_tr_b16 v[220:221], v194 offset:0x1e00
	v_exp_f32_e32 v236, v80
	v_exp_f32_e32 v237, v81
	v_exp_f32_e32 v238, v82
	s_waitcnt lgkmcnt(6)
	v_mfma_f32_32x32x16_bf16 v[32:47], v[162:165], v[222:225], v[32:47]
	ds_read_b64_tr_b16 v[222:223], v194 offset:0x2600
	ds_read_b64_tr_b16 v[224:225], v194 offset:0x2e00
	ds_read_b64_tr_b16 v[230:231], v194 offset:0x3600
	ds_read_b64_tr_b16 v[232:233], v194 offset:0x3e00
	v_exp_f32_e32 v239, v83
	v_exp_f32_e32 v240, v84
	v_exp_f32_e32 v241, v85
	s_waitcnt lgkmcnt(8)
	v_mfma_f32_32x32x16_bf16 v[32:47], v[166:169], v[226:229], v[32:47]
	v_exp_f32_e32 v242, v86
	v_exp_f32_e32 v243, v87
	v_exp_f32_e32 v244, v88
	s_waitcnt lgkmcnt(6)
	v_mfma_f32_32x32x16_bf16 v[16:31], v[210:213], v[214:217], v[16:31]
	v_exp_f32_e32 v245, v89
	v_exp_f32_e32 v246, v90
	v_exp_f32_e32 v247, v91
	s_waitcnt lgkmcnt(4)
	v_mfma_f32_32x32x16_bf16 v[16:31], v[170:173], v[218:221], v[16:31]
	v_exp_f32_e32 v248, v92
	v_exp_f32_e32 v249, v93
	v_exp_f32_e32 v250, v94
	s_waitcnt lgkmcnt(2)
	v_mfma_f32_32x32x16_bf16 v[16:31], v[162:165], v[222:225], v[16:31]
	v_exp_f32_e32 v251, v95
	s_waitcnt lgkmcnt(0)
	v_mfma_f32_32x32x16_bf16 v[16:31], v[166:169], v[230:233], v[16:31]
	s_barrier
	s_waitcnt vmcnt(4)
	v_cndmask_b32_e64 v210, v235, 1.0, s[2:3]
	v_cmp_gt_f32_e32 vcc, 1.0, v210
	s_waitcnt vmcnt(4)
	ds_write_b128 v197, v[128:131]
	ds_write_b128 v198, v[136:139]
	s_cbranch_vccz .LBB0_2127
	s_and_saveexec_b64 s[30:31], s[0:1]
	ds_write_b32 v191, v210 offset:128
	s_or_b64 exec, exec, s[30:31]
	s_waitcnt lgkmcnt(0)
	v_add_u32_e32 v174, v183, v176
	ds_read_b128 v[162:165], v174 offset:224
	ds_read_b128 v[166:169], v174 offset:192
	ds_read_b128 v[170:173], v174 offset:160
	ds_read_b128 v[212:215], v174 offset:128
	s_waitcnt lgkmcnt(3)
	v_pk_mul_f32 v[12:13], v[12:13], v[162:163]
	s_waitcnt lgkmcnt(2)
	v_pk_mul_f32 v[8:9], v[8:9], v[166:167]
	s_waitcnt lgkmcnt(1)
	v_pk_mul_f32 v[4:5], v[4:5], v[170:171]
	v_pk_mul_f32 v[14:15], v[14:15], v[164:165]
	v_pk_mul_f32 v[10:11], v[10:11], v[168:169]
	v_pk_mul_f32 v[6:7], v[6:7], v[172:173]
	s_waitcnt lgkmcnt(0)
	v_pk_mul_f32 v[2:3], v[2:3], v[214:215]
	v_pk_mul_f32 v[0:1], v[0:1], v[212:213]
	v_pk_mul_f32 v[60:61], v[60:61], v[162:163]
	v_pk_mul_f32 v[56:57], v[56:57], v[166:167]
	v_pk_mul_f32 v[52:53], v[52:53], v[170:171]
	v_pk_mul_f32 v[62:63], v[62:63], v[164:165]
	v_pk_mul_f32 v[58:59], v[58:59], v[168:169]
	v_pk_mul_f32 v[54:55], v[54:55], v[172:173]
	v_pk_mul_f32 v[50:51], v[50:51], v[214:215]
	v_pk_mul_f32 v[48:49], v[48:49], v[212:213]
	v_pk_mul_f32 v[44:45], v[44:45], v[162:163]
	v_pk_mul_f32 v[40:41], v[40:41], v[166:167]
	v_pk_mul_f32 v[36:37], v[36:37], v[170:171]
	v_pk_mul_f32 v[46:47], v[46:47], v[164:165]
	v_pk_mul_f32 v[42:43], v[42:43], v[168:169]
	v_pk_mul_f32 v[38:39], v[38:39], v[172:173]
	v_pk_mul_f32 v[34:35], v[34:35], v[214:215]
	v_pk_mul_f32 v[32:33], v[32:33], v[212:213]
	v_pk_mul_f32 v[28:29], v[28:29], v[162:163]
	v_pk_mul_f32 v[24:25], v[24:25], v[166:167]
	v_pk_mul_f32 v[20:21], v[20:21], v[170:171]
	v_pk_mul_f32 v[30:31], v[30:31], v[164:165]
	v_pk_mul_f32 v[26:27], v[26:27], v[168:169]
	v_pk_mul_f32 v[22:23], v[22:23], v[172:173]
	v_pk_mul_f32 v[18:19], v[18:19], v[214:215]
	v_pk_mul_f32 v[16:17], v[16:17], v[212:213]
; #define SBAR() __builtin_amdgcn_sched_barrier(0)
; #define SLOAD(i, k0) do { sr_[i].vs0 = *reinterpret_cast<const bf16x8*>(vptr + (size_t)((k0) + sr) * vstr); \
;     sr_[i].vs1 = *reinterpret_cast<const bf16x8*>(vptr + (size_t)((k0) + 32 + sr) * vstr); \
;     sr_[i].ks0 = *reinterpret_cast<const bf16x8*>(kptr + (size_t)((k0) + sr) * kstr); \
;     sr_[i].ks1 = *reinterpret_cast<const bf16x8*>(kptr + (size_t)((k0) + 32 + sr) * kstr); } while (0)
; #define RESC(a) do { if (__any((a) < 1.f)) { if (hi == 0) al_l[r32] = (a); asm volatile("s_waitcnt lgkmcnt(0)" ::: "memory"); \
;     _Pragma("unroll") for (int d = 0; d < NDV; ++d) _Pragma("unroll") for (int r = 0; r < 16; ++r) o[d][r] *= al_l[crow(r, hi)]; } } while (0)
; template <int NDQ, int NDV> ...
;     ...
;     RESC(alB); __syncthreads();
;     SBAR(); qkt<NDQ>(pA0, pA1, K_lds, qr, r32, hi);
;     finishSM(pB0, pB1, alB, l_reg, pa0, pa1, pa2, pa3); SBAR();
;     if (j + 3 < NT) SLOAD(SE, (j + 3) * 64); SBAR();
.LBB0_2127:
	v_mov_b32_e32 v211, v234
	v_fmamk_f32 v221, v64, 0x3e0293ee, v175
	v_fmamk_f32 v222, v65, 0x3e0293ee, v175
	v_fmamk_f32 v223, v66, 0x3e0293ee, v175
	v_fmamk_f32 v224, v67, 0x3e0293ee, v175
	v_fmamk_f32 v225, v68, 0x3e0293ee, v175
	v_fmamk_f32 v214, v69, 0x3e0293ee, v175
	v_fmamk_f32 v215, v70, 0x3e0293ee, v175
	v_fmamk_f32 v216, v71, 0x3e0293ee, v175
	v_fmamk_f32 v217, v72, 0x3e0293ee, v175
	v_fmamk_f32 v218, v73, 0x3e0293ee, v175
	v_fmamk_f32 v219, v74, 0x3e0293ee, v175
	v_fmamk_f32 v220, v75, 0x3e0293ee, v175
	v_fmamk_f32 v213, v76, 0x3e0293ee, v175
	v_fmamk_f32 v226, v77, 0x3e0293ee, v175
	v_fmamk_f32 v227, v78, 0x3e0293ee, v175
	v_fmamk_f32 v212, v79, 0x3e0293ee, v175
	s_add_i32 s61, s61, 2
	ds_read_b128 v[64:67], v199 offset:32768
	ds_read_b128 v[68:71], v199 offset:40960
	ds_read_b128 v[228:231], v200 offset:32768
	ds_read_b128 v[232:235], v200 offset:40960
	v_exp_f32_e32 v221, v221
	s_waitcnt lgkmcnt(3)
	v_mfma_f32_32x32x16_bf16 v[80:95], v[64:67], v[124:127], 0
	v_exp_f32_e32 v222, v222
	v_exp_f32_e32 v223, v223
	v_exp_f32_e32 v224, v224
	s_waitcnt lgkmcnt(2)
	v_mfma_f32_32x32x16_bf16 v[64:79], v[68:71], v[124:127], 0
	v_exp_f32_e32 v225, v225
	v_exp_f32_e32 v214, v214
	v_exp_f32_e32 v215, v215
	s_waitcnt lgkmcnt(1)
	v_mfma_f32_32x32x16_bf16 v[80:95], v[228:231], v[120:123], v[80:95]
	v_exp_f32_e32 v216, v216
	v_exp_f32_e32 v217, v217
	v_exp_f32_e32 v218, v218
	s_waitcnt lgkmcnt(0)
	v_mfma_f32_32x32x16_bf16 v[64:79], v[232:235], v[120:123], v[64:79]
	ds_read_b128 v[228:231], v201 offset:32768
	ds_read_b128 v[232:235], v201 offset:40960
	v_exp_f32_e32 v219, v219
	v_exp_f32_e32 v220, v220
	v_exp_f32_e32 v226, v226
	s_waitcnt lgkmcnt(1)
	v_mfma_f32_32x32x16_bf16 v[80:95], v[228:231], v[116:119], v[80:95]
	v_exp_f32_e32 v227, v227
	v_exp_f32_e32 v253, v212
	v_exp_f32_e32 v252, v213
	s_waitcnt lgkmcnt(0)
	v_mfma_f32_32x32x16_bf16 v[64:79], v[232:235], v[116:119], v[64:79]
	ds_read_b128 v[228:231], v202 offset:32768
	ds_read_b128 v[232:235], v202 offset:40960
	v_add_f32_e32 v212, 0, v236
	v_add_f32_e32 v212, v237, v212
	v_add_f32_e32 v212, v238, v212
	v_add_f32_e32 v212, v239, v212
	v_add_f32_e32 v212, v240, v212
	v_add_f32_e32 v212, v241, v212
	s_waitcnt lgkmcnt(1)
	v_mfma_f32_32x32x16_bf16 v[80:95], v[228:231], v[112:115], v[80:95]
	v_add_f32_e32 v212, v242, v212
	v_add_f32_e32 v212, v243, v212
	v_add_f32_e32 v212, v244, v212
	v_add_f32_e32 v212, v245, v212
	v_add_f32_e32 v212, v246, v212
	v_add_f32_e32 v212, v247, v212
	s_waitcnt lgkmcnt(0)
	v_mfma_f32_32x32x16_bf16 v[64:79], v[232:235], v[112:115], v[64:79]
	ds_read_b128 v[228:231], v203 offset:32768
	ds_read_b128 v[232:235], v203 offset:40960
	v_add_f32_e32 v212, v248, v212
	v_add_f32_e32 v212, v249, v212
	v_add_f32_e32 v212, v250, v212
	v_add_f32_e32 v212, v251, v212
	v_add_f32_e32 v212, v221, v212
	v_add_f32_e32 v212, v222, v212
	s_waitcnt lgkmcnt(1)
	v_mfma_f32_32x32x16_bf16 v[80:95], v[228:231], v[108:111], v[80:95]
	v_add_f32_e32 v212, v223, v212
	v_add_f32_e32 v212, v224, v212
	v_add_f32_e32 v212, v225, v212
	v_add_f32_e32 v212, v214, v212
	v_add_f32_e32 v212, v215, v212
	v_add_f32_e32 v212, v216, v212
	s_waitcnt lgkmcnt(0)
	v_mfma_f32_32x32x16_bf16 v[64:79], v[232:235], v[108:111], v[64:79]
	ds_read_b128 v[228:231], v204 offset:32768
	ds_read_b128 v[232:235], v204 offset:40960
	v_add_f32_e32 v212, v217, v212
	v_add_f32_e32 v212, v218, v212
	v_add_f32_e32 v212, v219, v212
	v_add_f32_e32 v212, v220, v212
	v_add_f32_e32 v212, v252, v212
	v_add_f32_e32 v212, v226, v212
	s_waitcnt lgkmcnt(1)
	v_mfma_f32_32x32x16_bf16 v[80:95], v[228:231], v[104:107], v[80:95]
	v_add_f32_e32 v212, v227, v212
	v_add_f32_e32 v212, v253, v212
	v_mov_b32_e32 v213, v212
	v_cvt_pk_bf16_f32 v160, v236, v237
	v_cvt_pk_bf16_f32 v161, v238, v239
	v_cvt_pk_bf16_f32 v162, v240, v241
	s_waitcnt lgkmcnt(0)
	v_mfma_f32_32x32x16_bf16 v[64:79], v[232:235], v[104:107], v[64:79]
	ds_read_b128 v[228:231], v205 offset:32768
	ds_read_b128 v[232:235], v205 offset:40960
	v_cvt_pk_bf16_f32 v163, v242, v243
	v_cvt_pk_bf16_f32 v164, v244, v245
	v_cvt_pk_bf16_f32 v165, v246, v247
	v_cvt_pk_bf16_f32 v166, v248, v249
	v_cvt_pk_bf16_f32 v167, v250, v251
	v_cvt_pk_bf16_f32 v168, v221, v222
	s_waitcnt lgkmcnt(1)
	v_mfma_f32_32x32x16_bf16 v[80:95], v[228:231], v[100:103], v[80:95]
	v_cvt_pk_bf16_f32 v169, v223, v224
	v_cvt_pk_bf16_f32 v170, v225, v214
	v_cvt_pk_bf16_f32 v171, v215, v216
	v_cvt_pk_bf16_f32 v172, v217, v218
	v_cvt_pk_bf16_f32 v173, v219, v220
	v_cvt_pk_bf16_f32 v174, v252, v226
	s_waitcnt lgkmcnt(0)
	v_mfma_f32_32x32x16_bf16 v[64:79], v[232:235], v[100:103], v[64:79]
	ds_read_b128 v[228:231], v206 offset:32768
	ds_read_b128 v[232:235], v206 offset:40960
	ds_read_b64_tr_b16 v[236:237], v193 offset:0
	ds_read_b64_tr_b16 v[238:239], v193 offset:0x800
	ds_read_b64_tr_b16 v[240:241], v193 offset:0x1000
	ds_read_b64_tr_b16 v[242:243], v193 offset:0x1800
	ds_read_b64_tr_b16 v[244:245], v193 offset:0x2000
	ds_read_b64_tr_b16 v[246:247], v193 offset:0x2800
	ds_read_b64_tr_b16 v[248:249], v193 offset:0x3000
	ds_read_b64_tr_b16 v[250:251], v193 offset:0x3800
	v_cvt_pk_bf16_f32 v175, v227, v253
	v_permlane32_swap_b32_e32 v212, v213
	v_permlane32_swap_b32_e32 v160, v162
	v_permlane32_swap_b32_e32 v161, v163
	v_permlane32_swap_b32_e32 v164, v166
	v_permlane32_swap_b32_e32 v165, v167
	s_waitcnt lgkmcnt(9)
	v_mfma_f32_32x32x16_bf16 v[80:95], v[228:231], v[96:99], v[80:95]
	v_permlane32_swap_b32_e32 v168, v170
	v_permlane32_swap_b32_e32 v169, v171
	v_permlane32_swap_b32_e32 v172, v174
	v_permlane32_swap_b32_e32 v173, v175
	s_waitcnt lgkmcnt(8)
	v_mfma_f32_32x32x16_bf16 v[64:79], v[232:235], v[96:99], v[64:79]
	s_cmpk_gt_u32 s61, 0x80
	s_cselect_b64 s[30:31], -1, 0
	s_and_b64 vcc, exec, s[30:31]
	s_cbranch_vccnz .LBB0_2129
	v_add_co_u32_e32 v132, vcc, 0xfffe8000, v184
	s_nop 1
	v_addc_co_u32_e32 v133, vcc, -1, v185, vcc
	global_load_dwordx4 v[128:131], v[132:133], off
	global_load_dwordx4 v[140:143], v[132:133], off offset:-512
	global_load_dwordx4 v[136:139], v[184:185], off
	s_nop 0
	global_load_dwordx4 v[132:135], v[184:185], off offset:-512

; #define SBAR() __builtin_amdgcn_sched_barrier(0)
; #define SLOAD(i, k0) do { sr_[i].vs0 = *reinterpret_cast<const bf16x8*>(vptr + (size_t)((k0) + sr) * vstr); \
;     sr_[i].vs1 = *reinterpret_cast<const bf16x8*>(vptr + (size_t)((k0) + 32 + sr) * vstr); \
;     sr_[i].ks0 = *reinterpret_cast<const bf16x8*>(kptr + (size_t)((k0) + sr) * kstr); \
;     sr_[i].ks1 = *reinterpret_cast<const bf16x8*>(kptr + (size_t)((k0) + 32 + sr) * kstr); } while (0)
; #define SWRITE(b, i) do { *(LAS bf16x8*)(V_lds + (b) * SHM_V + vst0) = sr_[i].vs0;          \
;     *(LAS bf16x8*)(V_lds + (b) * SHM_V + vst1) = sr_[i].vs1; const int kc = sc * 2;               \
;     *(LAS bf16x8*)(K_lds + (b) * SHM_K + KSWZ(sr, kc)) = sr_[i].ks0;                       \
;     *(LAS bf16x8*)(K_lds + (b) * SHM_K + KSWZ(32 + sr, kc)) = sr_[i].ks1; } while (0)
; #define SWAIT() asm volatile("s_waitcnt vmcnt(4)" ::: "memory")
; template <int NDQ, int NDV> ...
;     ...
;     if (j + 3 < NT) SLOAD(SE, (j + 3) * 64); SBAR();
;     pv_d0<NDV>(o, vb0 + SHM_V, pa0, pa1, pa2, pa3); partialSM(pA0, pA1, m_reg, mnA, alA, Cs, thr);
;     __syncthreads(); SWAIT(); SWRITE(1, SO);
.Lgqa_nodrain2:
	ds_write_b128 v195, v[148:151] offset:49152
	ds_write_b128 v196, v[152:155] offset:49152
	s_waitcnt lgkmcnt(8)
	v_mfma_f32_32x32x16_bf16 v[0:15], v[160:163], v[236:239], v[0:15]
	ds_read_b64_tr_b16 v[214:215], v193 offset:0x200
	ds_read_b64_tr_b16 v[216:217], v193 offset:0xa00
	v_max_f32_e32 v234, v81, v81
	v_max_f32_e32 v235, v80, v80
	v_max_f32_e32 v234, v235, v234
	v_max3_f32 v234, v234, v82, v83
	v_max3_f32 v234, v234, v84, v85
	v_max3_f32 v234, v234, v86, v87
	s_waitcnt lgkmcnt(8)
	v_mfma_f32_32x32x16_bf16 v[0:15], v[164:167], v[240:243], v[0:15]
	ds_read_b64_tr_b16 v[218:219], v193 offset:0x1200
	ds_read_b64_tr_b16 v[220:221], v193 offset:0x1a00
	v_max3_f32 v234, v234, v88, v89
	v_max3_f32 v234, v234, v90, v91
	v_max3_f32 v234, v234, v92, v93
	v_max3_f32 v234, v234, v94, v95
	v_max3_f32 v234, v234, v64, v65
	v_max3_f32 v234, v234, v66, v67
	s_waitcnt lgkmcnt(8)
	v_mfma_f32_32x32x16_bf16 v[0:15], v[168:171], v[244:247], v[0:15]
	ds_read_b64_tr_b16 v[222:223], v193 offset:0x2200
	ds_read_b64_tr_b16 v[224:225], v193 offset:0x2a00
	ds_read_b64_tr_b16 v[230:231], v193 offset:0x3200
	ds_read_b64_tr_b16 v[232:233], v193 offset:0x3a00
	v_max3_f32 v234, v234, v68, v69
	v_max3_f32 v234, v234, v70, v71
	v_max3_f32 v234, v234, v72, v73
	v_max3_f32 v234, v234, v74, v75
	v_max3_f32 v234, v234, v76, v77
	v_max3_f32 v234, v234, v78, v79
	s_waitcnt lgkmcnt(10)
	v_mfma_f32_32x32x16_bf16 v[0:15], v[172:175], v[248:251], v[0:15]
	v_mov_b32_e32 v235, v234
	s_nop 1
	v_permlane32_swap_b32_e32 v234, v235
	v_max_f32_e32 v235, v235, v235
	v_max_f32_e32 v234, v234, v234
	v_max_f32_e32 v234, v234, v235
	s_waitcnt lgkmcnt(6)
	v_mfma_f32_32x32x16_bf16 v[48:63], v[160:163], v[214:217], v[48:63]
	ds_read_b64_tr_b16 v[214:215], v193 offset:0x400
	ds_read_b64_tr_b16 v[216:217], v193 offset:0xc00
	v_max_f32_e32 v253, v211, v211
	v_sub_f32_e32 v235, v234, v211
	v_max_f32_e32 v234, v253, v234
	v_sub_f32_e32 v253, v211, v234
	v_mul_f32_e32 v253, 0x3e0293ee, v253
	s_waitcnt lgkmcnt(6)
	v_mfma_f32_32x32x16_bf16 v[48:63], v[164:167], v[218:221], v[48:63]
	ds_read_b64_tr_b16 v[218:219], v193 offset:0x1400
	ds_read_b64_tr_b16 v[220:221], v193 offset:0x1c00
	v_exp_f32_e32 v253, v253
	v_cmp_ge_f32_e32 vcc, s48, v235
	s_cmp_eq_u64 vcc, exec
	s_cselect_b64 s[2:3], -1, 0
	v_cndmask_b32_e64 v234, v234, v211, s[2:3]
	s_waitcnt lgkmcnt(6)
	v_mfma_f32_32x32x16_bf16 v[48:63], v[168:171], v[222:225], v[48:63]
	ds_read_b64_tr_b16 v[222:223], v193 offset:0x2400
	ds_read_b64_tr_b16 v[224:225], v193 offset:0x2c00
	ds_read_b64_tr_b16 v[226:227], v193 offset:0x3400
	ds_read_b64_tr_b16 v[228:229], v193 offset:0x3c00
	v_mul_f32_e32 v252, 0xbe0293ee, v234
	v_fmamk_f32 v80, v80, 0x3e0293ee, v252
	v_fmamk_f32 v81, v81, 0x3e0293ee, v252
	v_fmamk_f32 v82, v82, 0x3e0293ee, v252
	v_fmamk_f32 v83, v83, 0x3e0293ee, v252
	v_fmamk_f32 v84, v84, 0x3e0293ee, v252
	s_waitcnt lgkmcnt(8)
	v_mfma_f32_32x32x16_bf16 v[48:63], v[172:175], v[230:233], v[48:63]
	v_fmamk_f32 v85, v85, 0x3e0293ee, v252
	v_fmamk_f32 v86, v86, 0x3e0293ee, v252
	v_fmamk_f32 v87, v87, 0x3e0293ee, v252
	v_fmamk_f32 v88, v88, 0x3e0293ee, v252
	v_fmamk_f32 v89, v89, 0x3e0293ee, v252
	v_fmamk_f32 v90, v90, 0x3e0293ee, v252
	s_waitcnt lgkmcnt(6)
	v_mfma_f32_32x32x16_bf16 v[32:47], v[160:163], v[214:217], v[32:47]
	ds_read_b64_tr_b16 v[214:215], v193 offset:0x600
	ds_read_b64_tr_b16 v[216:217], v193 offset:0xe00
	v_fmamk_f32 v91, v91, 0x3e0293ee, v252
	v_fmamk_f32 v92, v92, 0x3e0293ee, v252
	v_fmamk_f32 v93, v93, 0x3e0293ee, v252
	v_fmamk_f32 v94, v94, 0x3e0293ee, v252
	v_fmamk_f32 v95, v95, 0x3e0293ee, v252
	s_waitcnt lgkmcnt(6)
	v_mfma_f32_32x32x16_bf16 v[32:47], v[164:167], v[218:221], v[32:47]
	ds_read_b64_tr_b16 v[218:219], v193 offset:0x1600
	ds_read_b64_tr_b16 v[220:221], v193 offset:0x1e00
	v_exp_f32_e32 v236, v80
	v_exp_f32_e32 v237, v81
	v_exp_f32_e32 v238, v82
	s_waitcnt lgkmcnt(6)
	v_mfma_f32_32x32x16_bf16 v[32:47], v[168:171], v[222:225], v[32:47]
	ds_read_b64_tr_b16 v[222:223], v193 offset:0x2600
	ds_read_b64_tr_b16 v[224:225], v193 offset:0x2e00
	ds_read_b64_tr_b16 v[230:231], v193 offset:0x3600
	ds_read_b64_tr_b16 v[232:233], v193 offset:0x3e00
	v_exp_f32_e32 v239, v83
	v_exp_f32_e32 v240, v84
	v_exp_f32_e32 v241, v85
	s_waitcnt lgkmcnt(8)
	v_mfma_f32_32x32x16_bf16 v[32:47], v[172:175], v[226:229], v[32:47]
	v_exp_f32_e32 v242, v86
	v_exp_f32_e32 v243, v87
	v_exp_f32_e32 v244, v88
	s_waitcnt lgkmcnt(6)
	v_mfma_f32_32x32x16_bf16 v[16:31], v[160:163], v[214:217], v[16:31]
	v_exp_f32_e32 v245, v89
	v_exp_f32_e32 v246, v90
	v_exp_f32_e32 v247, v91
	s_waitcnt lgkmcnt(4)
	v_mfma_f32_32x32x16_bf16 v[16:31], v[164:167], v[218:221], v[16:31]
	v_exp_f32_e32 v248, v92
	v_exp_f32_e32 v249, v93
	v_exp_f32_e32 v250, v94
	s_waitcnt lgkmcnt(2)
	v_mfma_f32_32x32x16_bf16 v[16:31], v[168:171], v[222:225], v[16:31]
	v_exp_f32_e32 v251, v95
	s_waitcnt lgkmcnt(0)
	v_mfma_f32_32x32x16_bf16 v[16:31], v[172:175], v[230:233], v[16:31]
	s_barrier
	s_waitcnt vmcnt(4)
	s_cmp_lg_u64 s[30:31], 0
	s_cbranch_scc0 .Lgqa_nodrain
	s_waitcnt vmcnt(0)
